# sample-attention loop: deferred softmax rescale (rescale O and l only when a row max grows by more than 8 in log2 units, same rule the prompt attention already uses)
# speedup vs baseline: 1.0040x; 1.0040x over previous
.LBB0_299:
	s_nop 10
	v_max3_f32 v96, v32, s31, v33
	v_max3_f32 v96, v96, v34, v35
	v_max3_f32 v96, v96, v36, v37
	v_max3_f32 v96, v96, v38, v39
	v_max3_f32 v96, v96, v40, v41
	v_max3_f32 v96, v96, v42, v43
	v_max3_f32 v96, v96, v44, v45
	v_max3_f32 v96, v96, v46, v47
	ds_bpermute_b32 v97, v194, v96
	s_waitcnt lgkmcnt(0)
	v_max3_f32 v104, v244, v96, v97
	v_add_f32_e32 v97, 0x41000000, v244
	v_cmp_gt_f32_e32 vcc, v104, v97
	s_cbranch_vccnz .Lsa_resc
	v_mov_b32_e32 v104, v244
	s_branch .LBB0_301
.Lsa_resc:
	v_sub_f32_e32 v96, v244, v104
	v_exp_f32_e32 v105, v96
	ds_bpermute_b32 v96, v164, v105
	ds_bpermute_b32 v97, v165, v105
	ds_bpermute_b32 v98, v166, v105
	ds_bpermute_b32 v99, v167, v105
	ds_bpermute_b32 v100, v162, v105
	ds_bpermute_b32 v101, v158, v105
	ds_bpermute_b32 v102, v156, v105
	ds_bpermute_b32 v106, v152, v105
	ds_bpermute_b32 v108, v148, v105
	ds_bpermute_b32 v110, v144, v105
	ds_bpermute_b32 v244, v140, v105
	ds_bpermute_b32 v245, v138, v105
	ds_bpermute_b32 v111, v142, v105
	ds_bpermute_b32 v109, v146, v105
	ds_bpermute_b32 v107, v150, v105
	ds_bpermute_b32 v103, v154, v105
	s_waitcnt lgkmcnt(4)
	v_pk_mul_f32 v[30:31], v[30:31], v[244:245]
	s_waitcnt lgkmcnt(3)
	v_pk_mul_f32 v[28:29], v[28:29], v[110:111]
	s_waitcnt lgkmcnt(2)
	v_pk_mul_f32 v[26:27], v[26:27], v[108:109]
	s_waitcnt lgkmcnt(1)
	v_pk_mul_f32 v[24:25], v[24:25], v[106:107]
	s_waitcnt lgkmcnt(0)
	v_pk_mul_f32 v[22:23], v[22:23], v[102:103]
	v_pk_mul_f32 v[20:21], v[20:21], v[100:101]
	v_pk_mul_f32 v[18:19], v[18:19], v[98:99]
	v_pk_mul_f32 v[16:17], v[16:17], v[96:97]
	v_pk_mul_f32 v[14:15], v[14:15], v[244:245]
	v_pk_mul_f32 v[12:13], v[12:13], v[110:111]
	v_pk_mul_f32 v[10:11], v[10:11], v[108:109]
	v_pk_mul_f32 v[8:9], v[8:9], v[106:107]
	v_pk_mul_f32 v[6:7], v[6:7], v[102:103]
	v_pk_mul_f32 v[4:5], v[4:5], v[100:101]
	v_pk_mul_f32 v[2:3], v[2:3], v[98:99]
	v_pk_mul_f32 v[0:1], v[0:1], v[96:97]
	v_mul_f32_e32 v169, v169, v105
